# scan: consumer waves at priority 1 (immediate-only change)
# speedup vs baseline: 1.0021x; 1.0021x over previous
; __device__ __forceinline__ void phase_scan2(const Params& p, int l, LAS unsigned char* lds) {
;     ...
;         auto consume = [&](int c, LAS const unsigned char* sl) {
;             const bf16x8 s0 = __builtin_bit_cast(bf16x8, (u32x4){pk_bf16(ST[0][0], ST[0][1]), pk_bf16(ST[0][2], ST[0][3]), pk_bf16(ST[1][0], ST[1][1]), pk_bf16(ST[1][2], ST[1][3])});
;             const bf16x8 s1 = __builtin_bit_cast(bf16x8, (u32x4){pk_bf16(ST[2][0], ST[2][1]), pk_bf16(ST[2][2], ST[2][3]), pk_bf16(ST[3][0], ST[3][1]), pk_bf16(ST[3][2], ST[3][3])});
;             const bf16x8 at0 = *(LAS const bf16x8*)(sl + SC_AT + (fr * 32 + fq * 8) * 2), at1 = *(LAS const bf16x8*)(sl + SC_AT + ((16 + fr) * 32 + fq * 8) * 2);
;             const bf16x8 rt0 = *(LAS const bf16x8*)(sl + SC_RT + (fr * 32 + fq * 8) * 2), rt1 = *(LAS const bf16x8*)(sl + SC_RT + ((16 + fr) * 32 + fq * 8) * 2);
;             const int mo = (fr * 16 + 4 * fq) * 2;
;             const bf16x8 vf = frag4(sl + SC_VP + mo), akf = frag4(sl + SC_AK + mo), xf = frag4(sl + SC_X + mo), rbf = frag4(sl + SC_RB + mo), rkf = frag4(sl + SC_RK + mo);
;             const f32x4 z = (f32x4){0.f, 0.f, 0.f, 0.f};
;             f32x4 g = __builtin_amdgcn_mfma_f32_16x16x32_bf16(at0, s0, z, 0, 0, 0);
;             g = __builtin_amdgcn_mfma_f32_16x16x32_bf16(at1, s1, g, 0, 0, 0);
;             g = __builtin_amdgcn_mfma_f32_16x16x32_bf16(akf, vf, g, 0, 0, 0);
;             const f32x4 sa = __builtin_amdgcn_mfma_f32_16x16x32_bf16(xf, cfrag(g), z, 0, 0, 0);
;             const bf16x8 saf = cfrag(sa);
;             f32x4 y = __builtin_amdgcn_mfma_f32_16x16x32_bf16(rt0, s0, z, 0, 0, 0);
;             y = __builtin_amdgcn_mfma_f32_16x16x32_bf16(rt1, s1, y, 0, 0, 0);
;             y = __builtin_amdgcn_mfma_f32_16x16x32_bf16(rbf, saf, y, 0, 0, 0);
;             y = __builtin_amdgcn_mfma_f32_16x16x32_bf16(rkf, vf, y, 0, 0, 0);
; #pragma unroll
;             for (int jt = 0; jt < 4; ++jt) {
;                 const f32x4 wc = *(LAS const f32x4*)(sl + SC_WC + (16 * jt + 4 * fq) * 4);
;                 const bf16x8 bb = frag4(sl + SC_BBT + ((16 * jt + fr) * SC_BS + 4 * fq) * 2), kb = frag4(sl + SC_KBT + ((16 * jt + fr) * SC_BS + 4 * fq) * 2);
;                 f32x4 acc = ST[jt];
;                 acc = __builtin_amdgcn_mfma_f32_16x16x32_bf16(bb, saf, acc, 0, 0, 0);
;                 acc = __builtin_amdgcn_mfma_f32_16x16x32_bf16(kb, vf, acc, 0, 0, 0);
.Lsc_consumer:
	s_setprio 1
	v_and_b32_e32 v4, 7, v1
	s_lshr_b32 s1, s25, 2
	v_xor_b32_e32 v4, v4, v2
	s_mul_i32 s0, s1, 768
	v_lshlrev_b32_e32 v4, 4, v4
	v_and_b32_e32 v5, 3, v1
	v_lshl_add_u32 v163, v1, 7, v4
	v_lshrrev_b32_e32 v4, 2, v1
	v_add_u32_e32 v13, s0, v6
	v_lshl_add_u32 v4, v2, 2, v4
	s_add_u32 s53, s53, s1
	v_and_b32_e32 v165, 7, v4
	s_mul_i32 s0, s54, 4096
	v_xor_b32_e32 v165, v165, v5
	s_lshl_b32 s0, s0, 10
	v_lshlrev_b32_e32 v165, 4, v165
	s_lshl_b32 s14, s52, 7
	v_lshl_add_u32 v165, v4, 7, v165
	s_lshl_b32 s15, s53, 5
	s_add_u32 s0, s0, s14
	v_lshlrev_b32_e32 v164, 5, v2
	v_add_u32_e32 v165, 4096, v165
	v_lshlrev_b32_e32 v166, 12, v2
	s_add_u32 s0, s0, s15
	s_add_u32 s0, s0, 0x5000000
	v_mov_b32_e32 v8, 0
	v_mov_b32_e32 v116, 0
	v_mov_b32_e32 v9, 0
	v_mov_b32_e32 v117, 0
	v_mov_b32_e32 v10, 0
	v_mov_b32_e32 v118, 0
	v_mov_b32_e32 v11, 0
	v_mov_b32_e32 v119, 0
	v_mov_b32_e32 v16, 0
	v_mov_b32_e32 v120, 0
	v_mov_b32_e32 v17, 0
	v_mov_b32_e32 v121, 0
	v_mov_b32_e32 v18, 0
	v_mov_b32_e32 v122, 0
	v_mov_b32_e32 v19, 0
	v_mov_b32_e32 v123, 0
	v_mov_b32_e32 v20, 0
	v_mov_b32_e32 v124, 0
	v_mov_b32_e32 v21, 0
	v_mov_b32_e32 v125, 0
	v_mov_b32_e32 v22, 0
	v_mov_b32_e32 v126, 0
	v_mov_b32_e32 v23, 0
	v_mov_b32_e32 v127, 0
	v_mov_b32_e32 v24, 0
	v_mov_b32_e32 v128, 0
	v_mov_b32_e32 v25, 0
	v_mov_b32_e32 v129, 0
	v_mov_b32_e32 v26, 0
	v_mov_b32_e32 v130, 0
	v_mov_b32_e32 v27, 0
	v_mov_b32_e32 v131, 0
	v_xor_b32_e32 v169, 64, v163
	v_add_u32_e32 v164, 10752, v164
	v_xor_b32_e32 v170, 64, v165
	v_lshl_add_u32 v166, v1, 1, v166
	s_add_u32 s48, s74, s0
	s_addc_u32 s49, s75, 0
	s_mov_b32 s42, 0
	s_mov_b32 s58, 0
	s_mov_b32 s56, 0
	s_branch .Lsc_c_bar
